# GROWS K-loop: LDS-DMA loads issued before the ds_reads inside each segment (head start against the counted vmcnt wait); on top of flips removal
# baseline (speedup 1.0000x reference)
; #define PG8_STAGE(bufoff, gbase, voff) do { _Pragma("unroll") for (int _i = 0; _i < 2; ++_i) \
;         __builtin_amdgcn_global_load_lds((const unsigned*)((const char*)(gbase) + (voff)[_i]), (PG8_LAS unsigned*)(lds + (bufoff) + ldsw + _i * 8192), 16, 0, 0); } while (0)
; #define PG8_LDA(dst, b, h) do { _Pragma("unroll") for (int m = 0; m < 4; ++m) _Pragma("unroll") for (int k = 0; k < 2; ++k) dst[m][k] = *(const PG8_LAS bf16x8*)(lds + PG8_SA(b, h) + aoff + m * 2048 + k * 1024); } while (0)
; #define PG8_LDB(dst, b, h) do { _Pragma("unroll") for (int n = 0; n < 2; ++n) _Pragma("unroll") for (int k = 0; k < 2; ++k) dst[n][k] = *(const PG8_LAS bf16x8*)(lds + PG8_SB(b, h) + boff + n * 2048 + k * 1024); } while (0)
; #define PG8_MMA(ai, bj, At, Bt) do { __builtin_amdgcn_s_setprio(1); _Pragma("unroll") for (int m = 0; m < 4; ++m) _Pragma("unroll") for (int n = 0; n < 2; ++n) _Pragma("unroll") for (int k = 0; k < 2; ++k) \
;         acc[ai][bj][m][n] = __builtin_amdgcn_mfma_f32_16x16x32_bf16(Bt[n][k], At[m][k], acc[ai][bj][m][n], 0, 0, 0); __builtin_amdgcn_s_setprio(0); } while (0)
; #define PG8_WAIT_V(n) asm volatile("s_waitcnt vmcnt(" #n ")" ::: "memory")
; #define PG8_WAIT_L(n) asm volatile("s_waitcnt lgkmcnt(" #n ")" ::: "memory")
; #define PG8_BAR __builtin_amdgcn_s_barrier()
; #define PG8_SCHED __builtin_amdgcn_sched_barrier(0)
; template <class Epi, class Sched, bool ALIGN_EPI = false, bool SP2 = false>
; __device__ __forceinline__ void gemm_phase(PG8_LAS unsigned char* lds, const Gemm g, const Sched& S, const Epi& E, const int tid) {
;     ...
;             const bool last = (t == nt - 2);
;             const char* a1 = cA + (size_t)(t + 1) * kstep;
;             const char* a2 = last ? nA : cA + (size_t)(t + 2) * kstep; const char* b2 = last ? nB : cB + (size_t)(t + 2) * kstep;
;             const char* a3 = a2 + kstep; const char* b3 = b2 + kstep;
;             if (last && has_next) S.a_ready(nxt);
;             if constexpr (SP2) {
;             PG8_LDB(B0, 0, 0); PG8_LDB(B1, 0, 1); PG8_SCHED; PG8_LDA(At, 0, 0); PG8_STAGE(PG8_SA(1, 1), a1 + hstep, voffA);
;             PG8_WAIT_V(8); PG8_WAIT_L(0); PG8_BAR; PG8_MMA(0, 0, At, B0); PG8_MMA(0, 1, At, B1); PG8_BAR; PG8_SCHED;
;             PG8_LDA(At, 0, 1); PG8_STAGE(PG8_SB(0, 0), b2, voffB); PG8_STAGE(PG8_SB(0, 1), b2 + hstep, voffB); PG8_STAGE(PG8_SA(0, 0), a2, voffA);
.LBB0_476:
	s_add_i32 s80, s58, 2
	s_add_u32 s81, s6, 0x80
	s_addc_u32 s59, s7, 0
	s_add_i32 s87, 0, 0x10000
	s_cmp_eq_u32 s70, s58
	s_cselect_b32 s59, s55, s59
	s_cselect_b32 s58, s54, s81
	s_cselect_b32 s83, s57, s79
	s_cselect_b32 s82, s56, s78
	s_add_i32 s81, 0, 0x14000
	v_lshl_add_u64 v[144:145], s[6:7], 0, v[170:171]
	s_add_i32 m0, s62, 0xc000
	s_nop 0
	global_load_lds_dwordx4 v[144:145], off
	v_lshl_add_u64 v[144:145], s[6:7], 0, v[172:173]
	s_add_i32 m0, s62, 0xe000
	s_nop 0
	global_load_lds_dwordx4 v[144:145], off
	v_add_u32_e32 v144, s87, v184
	ds_read_b128 v[132:135], v144
	ds_read_b128 v[136:139], v144 offset:1024
	ds_read_b128 v[140:143], v144 offset:2048
	ds_read_b128 v[174:177], v144 offset:3072
	v_add_u32_e32 v144, s81, v184
	ds_read_b128 v[178:181], v144
	ds_read_b128 v[188:191], v144 offset:1024
	ds_read_b128 v[192:195], v144 offset:2048
	ds_read_b128 v[196:199], v144 offset:3072
	ds_read_b128 v[200:203], v186
	ds_read_b128 v[204:207], v186 offset:1024
	ds_read_b128 v[208:211], v186 offset:2048
	ds_read_b128 v[212:215], v186 offset:3072
	ds_read_b128 v[216:219], v186 offset:4096
	ds_read_b128 v[220:223], v186 offset:5120
	ds_read_b128 v[224:227], v186 offset:6144
	ds_read_b128 v[238:241], v186 offset:7168
	s_waitcnt vmcnt(8)
	s_waitcnt lgkmcnt(0)
	s_barrier
	s_waitcnt lgkmcnt(0)
	v_mfma_f32_16x16x32_bf16 v[128:131], v[132:135], v[200:203], v[128:131]
	v_mfma_f32_16x16x32_bf16 v[124:127], v[140:143], v[200:203], v[124:127]
	v_mfma_f32_16x16x32_bf16 v[112:115], v[132:135], v[208:211], v[112:115]
	v_mfma_f32_16x16x32_bf16 v[108:111], v[140:143], v[208:211], v[108:111]
	v_mfma_f32_16x16x32_bf16 v[96:99], v[132:135], v[216:219], v[96:99]
	v_mfma_f32_16x16x32_bf16 v[92:95], v[140:143], v[216:219], v[92:95]
	v_mfma_f32_16x16x32_bf16 v[80:83], v[132:135], v[224:227], v[80:83]
	v_mfma_f32_16x16x32_bf16 v[76:79], v[140:143], v[224:227], v[76:79]
	v_mfma_f32_16x16x32_bf16 v[128:131], v[136:139], v[204:207], v[128:131]
	v_mfma_f32_16x16x32_bf16 v[124:127], v[174:177], v[204:207], v[124:127]
	v_mfma_f32_16x16x32_bf16 v[112:115], v[136:139], v[212:215], v[112:115]
	v_mfma_f32_16x16x32_bf16 v[108:111], v[174:177], v[212:215], v[108:111]
	v_mfma_f32_16x16x32_bf16 v[96:99], v[136:139], v[220:223], v[96:99]
	v_mfma_f32_16x16x32_bf16 v[92:95], v[174:177], v[220:223], v[92:95]
	v_mfma_f32_16x16x32_bf16 v[80:83], v[136:139], v[238:241], v[80:83]
	v_mfma_f32_16x16x32_bf16 v[76:79], v[174:177], v[238:241], v[76:79]
	v_mfma_f32_16x16x32_bf16 v[120:123], v[178:181], v[200:203], v[120:123]
	v_mfma_f32_16x16x32_bf16 v[116:119], v[192:195], v[200:203], v[116:119]
	v_mfma_f32_16x16x32_bf16 v[104:107], v[178:181], v[208:211], v[104:107]
	v_mfma_f32_16x16x32_bf16 v[100:103], v[192:195], v[208:211], v[100:103]
	v_mfma_f32_16x16x32_bf16 v[88:91], v[178:181], v[216:219], v[88:91]
	v_mfma_f32_16x16x32_bf16 v[84:87], v[192:195], v[216:219], v[84:87]
	v_mfma_f32_16x16x32_bf16 v[72:75], v[178:181], v[224:227], v[72:75]
	v_mfma_f32_16x16x32_bf16 v[68:71], v[192:195], v[224:227], v[68:71]
	v_mfma_f32_16x16x32_bf16 v[120:123], v[188:191], v[204:207], v[120:123]
	v_mfma_f32_16x16x32_bf16 v[116:119], v[196:199], v[204:207], v[116:119]
	v_mfma_f32_16x16x32_bf16 v[104:107], v[188:191], v[212:215], v[104:107]
	v_mfma_f32_16x16x32_bf16 v[100:103], v[196:199], v[212:215], v[100:103]
	v_mfma_f32_16x16x32_bf16 v[88:91], v[188:191], v[220:223], v[88:91]
	v_mfma_f32_16x16x32_bf16 v[84:87], v[196:199], v[220:223], v[84:87]
	v_mfma_f32_16x16x32_bf16 v[72:75], v[188:191], v[238:241], v[72:75]
	v_mfma_f32_16x16x32_bf16 v[68:71], v[196:199], v[238:241], v[68:71]
	s_barrier
	s_add_i32 s87, s87, s61
	v_lshl_add_u64 v[144:145], s[82:83], 0, v[146:147]
	s_mov_b32 m0, s87
	s_nop 0
	global_load_lds_dwordx4 v[144:145], off
	s_add_i32 m0, s87, 0x2000
	v_lshl_add_u64 v[242:243], s[82:83], 0, v[168:169]
	s_add_u32 s82, s82, s14
	s_addc_u32 s83, s83, 0
	s_add_i32 s81, s81, s61
	global_load_lds_dwordx4 v[242:243], off
	v_lshl_add_u64 v[244:245], s[82:83], 0, v[146:147]
	s_mov_b32 m0, s81
	v_lshl_add_u64 v[246:247], s[82:83], 0, v[168:169]
	global_load_lds_dwordx4 v[244:245], off
	s_add_i32 m0, s81, 0x2000
	v_lshl_add_u64 v[248:249], s[58:59], 0, v[0:1]
	global_load_lds_dwordx4 v[246:247], off
	s_mov_b32 m0, s62
	v_lshl_add_u64 v[148:149], s[58:59], 0, v[166:167]
	global_load_lds_dwordx4 v[248:249], off
	s_mov_b32 m0, s63
	s_nop 0
	global_load_lds_dwordx4 v[148:149], off
	ds_read_b128 v[200:203], v186 offset:16384
	ds_read_b128 v[204:207], v186 offset:17408
	ds_read_b128 v[208:211], v186 offset:18432
	ds_read_b128 v[212:215], v186 offset:19456
	ds_read_b128 v[216:219], v186 offset:20480
	ds_read_b128 v[220:223], v186 offset:21504
	ds_read_b128 v[224:227], v186 offset:22528
	ds_read_b128 v[238:241], v186 offset:23552
	s_waitcnt vmcnt(8)
	s_waitcnt lgkmcnt(0)
	s_barrier
; #define PG8_STAGE(bufoff, gbase, voff) do { _Pragma("unroll") for (int _i = 0; _i < 2; ++_i) \
;         __builtin_amdgcn_global_load_lds((const unsigned*)((const char*)(gbase) + (voff)[_i]), (PG8_LAS unsigned*)(lds + (bufoff) + ldsw + _i * 8192), 16, 0, 0); } while (0)
; #define PG8_LDA(dst, b, h) do { _Pragma("unroll") for (int m = 0; m < 4; ++m) _Pragma("unroll") for (int k = 0; k < 2; ++k) dst[m][k] = *(const PG8_LAS bf16x8*)(lds + PG8_SA(b, h) + aoff + m * 2048 + k * 1024); } while (0)
; #define PG8_LDB(dst, b, h) do { _Pragma("unroll") for (int n = 0; n < 2; ++n) _Pragma("unroll") for (int k = 0; k < 2; ++k) dst[n][k] = *(const PG8_LAS bf16x8*)(lds + PG8_SB(b, h) + boff + n * 2048 + k * 1024); } while (0)
; #define PG8_MMA(ai, bj, At, Bt) do { __builtin_amdgcn_s_setprio(1); _Pragma("unroll") for (int m = 0; m < 4; ++m) _Pragma("unroll") for (int n = 0; n < 2; ++n) _Pragma("unroll") for (int k = 0; k < 2; ++k) \
;         acc[ai][bj][m][n] = __builtin_amdgcn_mfma_f32_16x16x32_bf16(Bt[n][k], At[m][k], acc[ai][bj][m][n], 0, 0, 0); __builtin_amdgcn_s_setprio(0); } while (0)
; #define PG8_WAIT_V(n) asm volatile("s_waitcnt vmcnt(" #n ")" ::: "memory")
; #define PG8_WAIT_L(n) asm volatile("s_waitcnt lgkmcnt(" #n ")" ::: "memory")
; #define PG8_BAR __builtin_amdgcn_s_barrier()
; #define PG8_SCHED __builtin_amdgcn_sched_barrier(0)
; template <class Epi, class Sched, bool ALIGN_EPI = false, bool SP2 = false>
; __device__ __forceinline__ void gemm_phase(PG8_LAS unsigned char* lds, const Gemm g, const Sched& S, const Epi& E, const int tid) {
;     ...
;             PG8_WAIT_V(8); PG8_WAIT_L(0); PG8_BAR; PG8_MMA(1, 0, At, B0); PG8_MMA(1, 1, At, B1); PG8_BAR; PG8_SCHED;
;             PG8_LDB(B0, 1, 0); PG8_LDB(B1, 1, 1); PG8_SCHED; PG8_LDA(At, 1, 0); PG8_STAGE(PG8_SA(0, 1), a2 + hstep, voffA);
;             PG8_WAIT_V(8); PG8_WAIT_L(0); PG8_BAR; PG8_MMA(0, 0, At, B0); PG8_MMA(0, 1, At, B1); PG8_BAR; PG8_SCHED;
	s_waitcnt lgkmcnt(0)
	v_mfma_f32_16x16x32_bf16 v[64:67], v[132:135], v[200:203], v[64:67]
	v_mfma_f32_16x16x32_bf16 v[60:63], v[140:143], v[200:203], v[60:63]
	v_mfma_f32_16x16x32_bf16 v[48:51], v[132:135], v[208:211], v[48:51]
	v_mfma_f32_16x16x32_bf16 v[44:47], v[140:143], v[208:211], v[44:47]
	v_mfma_f32_16x16x32_bf16 v[32:35], v[132:135], v[216:219], v[32:35]
	v_mfma_f32_16x16x32_bf16 v[28:31], v[140:143], v[216:219], v[28:31]
	v_mfma_f32_16x16x32_bf16 v[16:19], v[132:135], v[224:227], v[16:19]
	v_mfma_f32_16x16x32_bf16 v[12:15], v[140:143], v[224:227], v[12:15]
	v_mfma_f32_16x16x32_bf16 v[64:67], v[136:139], v[204:207], v[64:67]
	v_mfma_f32_16x16x32_bf16 v[60:63], v[174:177], v[204:207], v[60:63]
	v_mfma_f32_16x16x32_bf16 v[48:51], v[136:139], v[212:215], v[48:51]
	v_mfma_f32_16x16x32_bf16 v[44:47], v[174:177], v[212:215], v[44:47]
	v_mfma_f32_16x16x32_bf16 v[32:35], v[136:139], v[220:223], v[32:35]
	v_mfma_f32_16x16x32_bf16 v[28:31], v[174:177], v[220:223], v[28:31]
	v_mfma_f32_16x16x32_bf16 v[16:19], v[136:139], v[238:241], v[16:19]
	v_mfma_f32_16x16x32_bf16 v[12:15], v[174:177], v[238:241], v[12:15]
	v_mfma_f32_16x16x32_bf16 v[56:59], v[178:181], v[200:203], v[56:59]
	v_mfma_f32_16x16x32_bf16 v[52:55], v[192:195], v[200:203], v[52:55]
	v_mfma_f32_16x16x32_bf16 v[40:43], v[178:181], v[208:211], v[40:43]
	v_mfma_f32_16x16x32_bf16 v[36:39], v[192:195], v[208:211], v[36:39]
	v_mfma_f32_16x16x32_bf16 v[24:27], v[178:181], v[216:219], v[24:27]
	v_mfma_f32_16x16x32_bf16 v[20:23], v[192:195], v[216:219], v[20:23]
	v_mfma_f32_16x16x32_bf16 v[8:11], v[178:181], v[224:227], v[8:11]
	v_mfma_f32_16x16x32_bf16 v[4:7], v[192:195], v[224:227], v[4:7]
	v_mfma_f32_16x16x32_bf16 v[56:59], v[188:191], v[204:207], v[56:59]
	v_mfma_f32_16x16x32_bf16 v[52:55], v[196:199], v[204:207], v[52:55]
	v_mfma_f32_16x16x32_bf16 v[40:43], v[188:191], v[212:215], v[40:43]
	v_mfma_f32_16x16x32_bf16 v[36:39], v[196:199], v[212:215], v[36:39]
	v_mfma_f32_16x16x32_bf16 v[24:27], v[188:191], v[220:223], v[24:27]
	v_mfma_f32_16x16x32_bf16 v[20:23], v[196:199], v[220:223], v[20:23]
	v_mfma_f32_16x16x32_bf16 v[8:11], v[188:191], v[238:241], v[8:11]
	v_mfma_f32_16x16x32_bf16 v[4:7], v[196:199], v[238:241], v[4:7]
	s_barrier
	s_add_i32 s81, 0, 0x18000
	s_add_i32 s82, 0, 0x1c000
	s_add_u32 s58, s58, s14
	s_addc_u32 s59, s59, 0
	s_mov_b32 m0, s64
	v_lshl_add_u64 v[150:151], s[58:59], 0, v[0:1]
	global_load_lds_dwordx4 v[150:151], off
	v_lshl_add_u64 v[150:151], s[58:59], 0, v[166:167]
	s_mov_b32 m0, s65
	s_nop 0
	global_load_lds_dwordx4 v[150:151], off
	v_add_u32_e32 v150, s81, v184
	ds_read_b128 v[132:135], v150
	ds_read_b128 v[136:139], v150 offset:1024
	ds_read_b128 v[140:143], v150 offset:2048
	ds_read_b128 v[174:177], v150 offset:3072
	v_add_u32_e32 v150, s82, v184
	ds_read_b128 v[178:181], v150
	ds_read_b128 v[188:191], v150 offset:1024
	ds_read_b128 v[192:195], v150 offset:2048
	ds_read_b128 v[196:199], v150 offset:3072
	ds_read_b128 v[200:203], v186 offset:32768
	ds_read_b128 v[204:207], v186 offset:33792
	ds_read_b128 v[208:211], v186 offset:34816
	ds_read_b128 v[212:215], v186 offset:35840
	ds_read_b128 v[216:219], v186 offset:36864
	ds_read_b128 v[220:223], v186 offset:37888
	ds_read_b128 v[224:227], v186 offset:38912
	ds_read_b128 v[238:241], v186 offset:39936
	s_waitcnt vmcnt(8)
	s_waitcnt lgkmcnt(0)
	s_barrier
	s_waitcnt lgkmcnt(0)
	v_mfma_f32_16x16x32_bf16 v[128:131], v[132:135], v[200:203], v[128:131]
	v_mfma_f32_16x16x32_bf16 v[124:127], v[140:143], v[200:203], v[124:127]
	v_mfma_f32_16x16x32_bf16 v[112:115], v[132:135], v[208:211], v[112:115]
	v_mfma_f32_16x16x32_bf16 v[108:111], v[140:143], v[208:211], v[108:111]
	v_mfma_f32_16x16x32_bf16 v[96:99], v[132:135], v[216:219], v[96:99]
	v_mfma_f32_16x16x32_bf16 v[92:95], v[140:143], v[216:219], v[92:95]
	v_mfma_f32_16x16x32_bf16 v[80:83], v[132:135], v[224:227], v[80:83]
	v_mfma_f32_16x16x32_bf16 v[76:79], v[140:143], v[224:227], v[76:79]
	v_mfma_f32_16x16x32_bf16 v[128:131], v[136:139], v[204:207], v[128:131]
	v_mfma_f32_16x16x32_bf16 v[124:127], v[174:177], v[204:207], v[124:127]
	v_mfma_f32_16x16x32_bf16 v[112:115], v[136:139], v[212:215], v[112:115]
	v_mfma_f32_16x16x32_bf16 v[108:111], v[174:177], v[212:215], v[108:111]
	v_mfma_f32_16x16x32_bf16 v[96:99], v[136:139], v[220:223], v[96:99]
	v_mfma_f32_16x16x32_bf16 v[92:95], v[174:177], v[220:223], v[92:95]
	v_mfma_f32_16x16x32_bf16 v[80:83], v[136:139], v[238:241], v[80:83]
	v_mfma_f32_16x16x32_bf16 v[76:79], v[174:177], v[238:241], v[76:79]
	v_mfma_f32_16x16x32_bf16 v[120:123], v[178:181], v[200:203], v[120:123]
	v_mfma_f32_16x16x32_bf16 v[116:119], v[192:195], v[200:203], v[116:119]
	v_mfma_f32_16x16x32_bf16 v[104:107], v[178:181], v[208:211], v[104:107]
	v_mfma_f32_16x16x32_bf16 v[100:103], v[192:195], v[208:211], v[100:103]
	v_mfma_f32_16x16x32_bf16 v[88:91], v[178:181], v[216:219], v[88:91]
	v_mfma_f32_16x16x32_bf16 v[84:87], v[192:195], v[216:219], v[84:87]
	v_mfma_f32_16x16x32_bf16 v[72:75], v[178:181], v[224:227], v[72:75]
	v_mfma_f32_16x16x32_bf16 v[68:71], v[192:195], v[224:227], v[68:71]
	v_mfma_f32_16x16x32_bf16 v[120:123], v[188:191], v[204:207], v[120:123]
	v_mfma_f32_16x16x32_bf16 v[116:119], v[196:199], v[204:207], v[116:119]
	v_mfma_f32_16x16x32_bf16 v[104:107], v[188:191], v[212:215], v[104:107]
	v_mfma_f32_16x16x32_bf16 v[100:103], v[196:199], v[212:215], v[100:103]
	v_mfma_f32_16x16x32_bf16 v[88:91], v[188:191], v[220:223], v[88:91]
	v_mfma_f32_16x16x32_bf16 v[84:87], v[196:199], v[220:223], v[84:87]
	v_mfma_f32_16x16x32_bf16 v[72:75], v[188:191], v[238:241], v[72:75]
	v_mfma_f32_16x16x32_bf16 v[68:71], v[196:199], v[238:241], v[68:71]
	s_barrier
; #define PG8_STAGE(bufoff, gbase, voff) do { _Pragma("unroll") for (int _i = 0; _i < 2; ++_i) \
;         __builtin_amdgcn_global_load_lds((const unsigned*)((const char*)(gbase) + (voff)[_i]), (PG8_LAS unsigned*)(lds + (bufoff) + ldsw + _i * 8192), 16, 0, 0); } while (0)
; #define PG8_LDA(dst, b, h) do { _Pragma("unroll") for (int m = 0; m < 4; ++m) _Pragma("unroll") for (int k = 0; k < 2; ++k) dst[m][k] = *(const PG8_LAS bf16x8*)(lds + PG8_SA(b, h) + aoff + m * 2048 + k * 1024); } while (0)
; #define PG8_MMA(ai, bj, At, Bt) do { __builtin_amdgcn_s_setprio(1); _Pragma("unroll") for (int m = 0; m < 4; ++m) _Pragma("unroll") for (int n = 0; n < 2; ++n) _Pragma("unroll") for (int k = 0; k < 2; ++k) \
;         acc[ai][bj][m][n] = __builtin_amdgcn_mfma_f32_16x16x32_bf16(Bt[n][k], At[m][k], acc[ai][bj][m][n], 0, 0, 0); __builtin_amdgcn_s_setprio(0); } while (0)
; #define PG8_WAIT_V(n) asm volatile("s_waitcnt vmcnt(" #n ")" ::: "memory")
; #define PG8_WAIT_L(n) asm volatile("s_waitcnt lgkmcnt(" #n ")" ::: "memory")
; #define PG8_BAR __builtin_amdgcn_s_barrier()
; #define PG8_SCHED __builtin_amdgcn_sched_barrier(0)
; template <class Epi, class Sched, bool ALIGN_EPI = false, bool SP2 = false>
; __device__ __forceinline__ void gemm_phase(PG8_LAS unsigned char* lds, const Gemm g, const Sched& S, const Epi& E, const int tid) {
;     ...
;             PG8_LDA(At, 1, 1); PG8_STAGE(PG8_SB(1, 0), b3, voffB); PG8_STAGE(PG8_SB(1, 1), b3 + hstep, voffB); PG8_STAGE(PG8_SA(1, 0), a3, voffA);
;             PG8_WAIT_V(8); PG8_WAIT_L(0); PG8_BAR; PG8_MMA(1, 0, At, B0); PG8_MMA(1, 1, At, B1); PG8_BAR; PG8_SCHED;
;     ...
;         if constexpr (ALIGN_EPI) { if (wr == 0) PG8_BAR; }
	s_add_i32 s58, s81, s61
	v_lshl_add_u64 v[144:145], v[144:145], 0, s[0:1]
	s_mov_b32 m0, s58
	s_nop 0
	global_load_lds_dwordx4 v[144:145], off
	v_lshl_add_u64 v[144:145], v[242:243], 0, s[0:1]
	s_add_i32 m0, s58, 0x2000
	s_add_i32 s58, s82, s61
	global_load_lds_dwordx4 v[144:145], off
	v_lshl_add_u64 v[144:145], v[244:245], 0, s[0:1]
	s_mov_b32 m0, s58
	s_nop 0
	global_load_lds_dwordx4 v[144:145], off
	v_lshl_add_u64 v[144:145], v[246:247], 0, s[0:1]
	s_add_i32 m0, s58, 0x2000
	s_nop 0
	global_load_lds_dwordx4 v[144:145], off
	v_lshl_add_u64 v[144:145], v[248:249], 0, s[0:1]
	s_mov_b32 m0, s66
	s_nop 0
	global_load_lds_dwordx4 v[144:145], off
	v_lshl_add_u64 v[144:145], v[148:149], 0, s[0:1]
	s_mov_b32 m0, s67
	s_nop 0
	global_load_lds_dwordx4 v[144:145], off
	ds_read_b128 v[200:203], v186 offset:49152
	ds_read_b128 v[204:207], v186 offset:50176
	ds_read_b128 v[208:211], v186 offset:51200
	ds_read_b128 v[212:215], v186 offset:52224
	ds_read_b128 v[216:219], v186 offset:53248
	ds_read_b128 v[220:223], v186 offset:54272
	ds_read_b128 v[224:227], v186 offset:55296
	ds_read_b128 v[238:241], v186 offset:56320
	s_waitcnt vmcnt(8)
	s_waitcnt lgkmcnt(0)
	s_barrier
	s_waitcnt lgkmcnt(0)
	v_mfma_f32_16x16x32_bf16 v[64:67], v[132:135], v[200:203], v[64:67]
	v_mfma_f32_16x16x32_bf16 v[60:63], v[140:143], v[200:203], v[60:63]
	v_mfma_f32_16x16x32_bf16 v[48:51], v[132:135], v[208:211], v[48:51]
	v_mfma_f32_16x16x32_bf16 v[44:47], v[140:143], v[208:211], v[44:47]
	v_mfma_f32_16x16x32_bf16 v[32:35], v[132:135], v[216:219], v[32:35]
	v_mfma_f32_16x16x32_bf16 v[28:31], v[140:143], v[216:219], v[28:31]
	v_mfma_f32_16x16x32_bf16 v[16:19], v[132:135], v[224:227], v[16:19]
	v_mfma_f32_16x16x32_bf16 v[12:15], v[140:143], v[224:227], v[12:15]
	v_mfma_f32_16x16x32_bf16 v[64:67], v[136:139], v[204:207], v[64:67]
	v_mfma_f32_16x16x32_bf16 v[60:63], v[174:177], v[204:207], v[60:63]
	v_mfma_f32_16x16x32_bf16 v[48:51], v[136:139], v[212:215], v[48:51]
	v_mfma_f32_16x16x32_bf16 v[44:47], v[174:177], v[212:215], v[44:47]
	v_mfma_f32_16x16x32_bf16 v[32:35], v[136:139], v[220:223], v[32:35]
	v_mfma_f32_16x16x32_bf16 v[28:31], v[174:177], v[220:223], v[28:31]
	v_mfma_f32_16x16x32_bf16 v[16:19], v[136:139], v[238:241], v[16:19]
	v_mfma_f32_16x16x32_bf16 v[12:15], v[174:177], v[238:241], v[12:15]
	v_mfma_f32_16x16x32_bf16 v[56:59], v[178:181], v[200:203], v[56:59]
	v_mfma_f32_16x16x32_bf16 v[52:55], v[192:195], v[200:203], v[52:55]
	v_mfma_f32_16x16x32_bf16 v[40:43], v[178:181], v[208:211], v[40:43]
	v_mfma_f32_16x16x32_bf16 v[36:39], v[192:195], v[208:211], v[36:39]
	v_mfma_f32_16x16x32_bf16 v[24:27], v[178:181], v[216:219], v[24:27]
	v_mfma_f32_16x16x32_bf16 v[20:23], v[192:195], v[216:219], v[20:23]
	v_mfma_f32_16x16x32_bf16 v[8:11], v[178:181], v[224:227], v[8:11]
	v_mfma_f32_16x16x32_bf16 v[4:7], v[192:195], v[224:227], v[4:7]
	v_mfma_f32_16x16x32_bf16 v[56:59], v[188:191], v[204:207], v[56:59]
	v_mfma_f32_16x16x32_bf16 v[52:55], v[196:199], v[204:207], v[52:55]
	v_mfma_f32_16x16x32_bf16 v[40:43], v[188:191], v[212:215], v[40:43]
	v_mfma_f32_16x16x32_bf16 v[36:39], v[196:199], v[212:215], v[36:39]
	v_mfma_f32_16x16x32_bf16 v[24:27], v[188:191], v[220:223], v[24:27]
	v_mfma_f32_16x16x32_bf16 v[20:23], v[196:199], v[220:223], v[20:23]
	v_mfma_f32_16x16x32_bf16 v[8:11], v[188:191], v[238:241], v[8:11]
	v_mfma_f32_16x16x32_bf16 v[4:7], v[196:199], v[238:241], v[4:7]
	s_barrier
	s_add_u32 s6, s6, 0x100
	s_addc_u32 s7, s7, 0
	s_add_u32 s78, s78, 0x100
	s_addc_u32 s79, s79, 0
	s_cmp_ge_u32 s80, s69
	s_mov_b32 s58, s80
	s_cbranch_scc0 .LBB0_476
	s_and_b64 vcc, exec, s[50:51]
	s_cbranch_vccz .LBB0_479
	s_barrier
